# MLA attention loop software-pipelined by one tile: QK(t) MFMAs hide softmax exp/sum/cvt of tile t-1, P.V(t-1) MFMAs hide row max of tile t; two score register sets, loop unrolled x2, 5 LDS fragment se
# speedup vs baseline: 1.0120x; 1.0031x over previous
.Lskip_v2_2_p0:
.LBB0_2155_p0:
	s_sub_i32 s61, s75, 63
	s_cmp_gt_i32 s61, s25
	s_cbranch_scc1 .Lnovis_p0
	s_bitcmp1_b32 s60, 0
	s_cselect_b32 s60, 0x6400, 0
	v_add_u32_e32 v0, s60, v200
	s_setprio 1
	ds_read_b128 v[238:241], v0
	ds_read_b128 v[244:247], v0 offset:32
	ds_read_b128 v[248:251], v0 offset:12800
	ds_read_b128 v[8:11], v0 offset:12832
	ds_read_b128 v[12:15], v0 offset:64
	s_waitcnt lgkmcnt(4)
	v_mfma_f32_32x32x16_bf16 v[96:111], v[238:241], v[128:131], v[80:95]
	ds_read_b128 v[238:241], v0 offset:12864
	s_waitcnt lgkmcnt(4)
	v_mfma_f32_32x32x16_bf16 v[96:111], v[244:247], v[132:135], v[96:111]
	ds_read_b128 v[244:247], v0 offset:96
	s_waitcnt lgkmcnt(4)
	v_mfma_f32_32x32x16_bf16 v[112:127], v[248:251], v[128:131], v[80:95]
	ds_read_b128 v[248:251], v0 offset:12896
	s_waitcnt lgkmcnt(4)
	v_mfma_f32_32x32x16_bf16 v[112:127], v[8:11], v[132:135], v[112:127]
	ds_read_b128 v[8:11], v0 offset:128
	s_waitcnt lgkmcnt(4)
	v_mfma_f32_32x32x16_bf16 v[96:111], v[12:15], v[136:139], v[96:111]
	ds_read_b128 v[12:15], v0 offset:12928
	s_waitcnt lgkmcnt(4)
	v_mfma_f32_32x32x16_bf16 v[112:127], v[238:241], v[136:139], v[112:127]
	ds_read_b128 v[238:241], v0 offset:160
	s_waitcnt lgkmcnt(4)
	v_mfma_f32_32x32x16_bf16 v[96:111], v[244:247], v[140:143], v[96:111]
	ds_read_b128 v[244:247], v0 offset:12960
	s_waitcnt lgkmcnt(4)
	v_mfma_f32_32x32x16_bf16 v[112:127], v[248:251], v[140:143], v[112:127]
	ds_read_b128 v[248:251], v0 offset:192
	s_waitcnt lgkmcnt(4)
	v_mfma_f32_32x32x16_bf16 v[96:111], v[8:11], v[144:147], v[96:111]
	ds_read_b128 v[8:11], v0 offset:12992
	s_waitcnt lgkmcnt(4)
	v_mfma_f32_32x32x16_bf16 v[112:127], v[12:15], v[144:147], v[112:127]
	ds_read_b128 v[12:15], v0 offset:224
	s_waitcnt lgkmcnt(4)
	v_mfma_f32_32x32x16_bf16 v[96:111], v[238:241], v[148:151], v[96:111]
	ds_read_b128 v[238:241], v0 offset:13024
	s_waitcnt lgkmcnt(4)
	v_mfma_f32_32x32x16_bf16 v[112:127], v[244:247], v[148:151], v[112:127]
	ds_read_b128 v[244:247], v0 offset:256
	s_waitcnt lgkmcnt(4)
	v_mfma_f32_32x32x16_bf16 v[96:111], v[248:251], v[152:155], v[96:111]
	ds_read_b128 v[248:251], v0 offset:13056
	s_waitcnt lgkmcnt(4)
	v_mfma_f32_32x32x16_bf16 v[112:127], v[8:11], v[152:155], v[112:127]
	ds_read_b128 v[8:11], v0 offset:288
	s_waitcnt lgkmcnt(4)
	v_mfma_f32_32x32x16_bf16 v[96:111], v[12:15], v[156:159], v[96:111]
	ds_read_b128 v[12:15], v0 offset:13088
	s_waitcnt lgkmcnt(4)
	v_mfma_f32_32x32x16_bf16 v[112:127], v[238:241], v[156:159], v[112:127]
	ds_read_b128 v[238:241], v0 offset:320
	s_waitcnt lgkmcnt(4)
	v_mfma_f32_32x32x16_bf16 v[96:111], v[244:247], v[160:163], v[96:111]
	ds_read_b128 v[244:247], v0 offset:13120
	s_waitcnt lgkmcnt(4)
	v_mfma_f32_32x32x16_bf16 v[112:127], v[248:251], v[160:163], v[112:127]
	ds_read_b128 v[248:251], v0 offset:352
	s_waitcnt lgkmcnt(4)
	v_mfma_f32_32x32x16_bf16 v[96:111], v[8:11], v[164:167], v[96:111]
	ds_read_b128 v[8:11], v0 offset:13152
	s_waitcnt lgkmcnt(4)
	v_mfma_f32_32x32x16_bf16 v[112:127], v[12:15], v[164:167], v[112:127]
	s_waitcnt lgkmcnt(3)
	v_mfma_f32_32x32x16_bf16 v[96:111], v[238:241], v[168:171], v[96:111]
	s_waitcnt lgkmcnt(2)
	v_mfma_f32_32x32x16_bf16 v[112:127], v[244:247], v[168:171], v[112:127]
	s_waitcnt lgkmcnt(1)
	v_mfma_f32_32x32x16_bf16 v[96:111], v[248:251], v[172:175], v[96:111]
	s_waitcnt lgkmcnt(0)
	v_mfma_f32_32x32x16_bf16 v[112:127], v[8:11], v[172:175], v[112:127]
	s_setprio 0
	s_cmp_le_i32 s75, s68
	s_cbranch_scc1 .Lmaskdone_p0
	v_add_u32_e32 v0, s75, v201
	v_subrev_u32_e32 v4, 31, v0
	v_subrev_u32_e32 v3, 63, v0
	v_cmp_le_i32_e32 vcc, v4, v197
	s_nop 4
	v_cndmask_b32_e32 v112, v194, v112, vcc
	v_cmp_lt_i32_e32 vcc, v3, v197
	s_nop 1
	v_cndmask_b32_e32 v97, v194, v97, vcc
	v_cmp_le_i32_e32 vcc, v3, v197
	v_subrev_u32_e32 v3, 30, v0
	s_nop 0
	v_cndmask_b32_e32 v96, v194, v96, vcc
	v_cmp_le_i32_e32 vcc, v3, v197
	v_subrev_u32_e32 v3, 61, v0
	s_nop 0
	v_cndmask_b32_e32 v113, v194, v113, vcc
	v_cmp_le_i32_e32 vcc, v3, v197
	v_subrev_u32_e32 v3, 29, v0
	s_nop 0
	v_cndmask_b32_e32 v98, v194, v98, vcc
	v_cmp_le_i32_e32 vcc, v3, v197
	v_subrev_u32_e32 v3, 60, v0
	s_nop 0
	v_cndmask_b32_e32 v114, v194, v114, vcc
	v_cmp_le_i32_e32 vcc, v3, v197
	v_subrev_u32_e32 v3, 28, v0
	s_nop 0
	v_cndmask_b32_e32 v99, v194, v99, vcc
	v_cmp_le_i32_e32 vcc, v3, v197
	v_subrev_u32_e32 v3, 55, v0
	s_nop 0
	v_cndmask_b32_e32 v115, v194, v115, vcc
	v_cmp_le_i32_e32 vcc, v3, v197
	v_subrev_u32_e32 v3, 23, v0
	s_nop 0
	v_cndmask_b32_e32 v100, v194, v100, vcc
	v_cmp_le_i32_e32 vcc, v3, v197
	v_subrev_u32_e32 v3, 54, v0
	s_nop 0
	v_cndmask_b32_e32 v116, v194, v116, vcc
	v_cmp_le_i32_e32 vcc, v3, v197
	v_subrev_u32_e32 v3, 22, v0
	s_nop 0
	v_cndmask_b32_e32 v101, v194, v101, vcc
	v_cmp_le_i32_e32 vcc, v3, v197
	v_subrev_u32_e32 v3, 53, v0
	s_nop 0
	v_cndmask_b32_e32 v117, v194, v117, vcc
	v_cmp_le_i32_e32 vcc, v3, v197
	v_subrev_u32_e32 v3, 21, v0
	s_nop 0
	v_cndmask_b32_e32 v102, v194, v102, vcc
	v_cmp_le_i32_e32 vcc, v3, v197
	v_subrev_u32_e32 v3, 52, v0
	s_nop 0
	v_cndmask_b32_e32 v118, v194, v118, vcc
	v_cmp_le_i32_e32 vcc, v3, v197
	v_subrev_u32_e32 v3, 20, v0
	s_nop 0
	v_cndmask_b32_e32 v103, v194, v103, vcc
	v_cmp_le_i32_e32 vcc, v3, v197
	v_subrev_u32_e32 v3, 47, v0
	s_nop 0
	v_cndmask_b32_e32 v119, v194, v119, vcc
	v_cmp_le_i32_e32 vcc, v3, v197
	v_add_u32_e32 v3, -15, v0
	s_nop 0
	v_cndmask_b32_e32 v104, v194, v104, vcc
	v_cmp_le_i32_e32 vcc, v3, v197
	v_subrev_u32_e32 v3, 46, v0
	s_nop 0
	v_cndmask_b32_e32 v120, v194, v120, vcc
	v_cmp_le_i32_e32 vcc, v3, v197
	v_add_u32_e32 v3, -14, v0
	s_nop 0
	v_cndmask_b32_e32 v105, v194, v105, vcc
	v_cmp_le_i32_e32 vcc, v3, v197
	v_subrev_u32_e32 v3, 45, v0
	s_nop 0
	v_cndmask_b32_e32 v121, v194, v121, vcc
	v_cmp_le_i32_e32 vcc, v3, v197
	v_add_u32_e32 v3, -13, v0
	s_nop 0
	v_cndmask_b32_e32 v106, v194, v106, vcc
	v_cmp_le_i32_e32 vcc, v3, v197
	v_subrev_u32_e32 v3, 44, v0
	s_nop 0
	v_cndmask_b32_e32 v122, v194, v122, vcc
	v_cmp_le_i32_e32 vcc, v3, v197
	v_add_u32_e32 v3, -12, v0
	s_nop 0
	v_cndmask_b32_e32 v107, v194, v107, vcc
	v_cmp_le_i32_e32 vcc, v3, v197
	v_subrev_u32_e32 v3, 39, v0
	s_nop 0
	v_cndmask_b32_e32 v123, v194, v123, vcc
	v_cmp_le_i32_e32 vcc, v3, v197
	v_add_u32_e32 v3, -7, v0
	s_nop 0
	v_cndmask_b32_e32 v108, v194, v108, vcc
	v_cmp_le_i32_e32 vcc, v3, v197
	v_subrev_u32_e32 v3, 38, v0
	s_nop 0
	v_cndmask_b32_e32 v124, v194, v124, vcc
	v_cmp_le_i32_e32 vcc, v3, v197
	v_add_u32_e32 v3, -6, v0
	s_nop 0
	v_cndmask_b32_e32 v109, v194, v109, vcc
	v_cmp_le_i32_e32 vcc, v3, v197
	v_subrev_u32_e32 v3, 37, v0
	s_nop 0
	v_cndmask_b32_e32 v125, v194, v125, vcc
	v_cmp_le_i32_e32 vcc, v3, v197
	v_add_u32_e32 v3, -5, v0
	s_nop 0
	v_cndmask_b32_e32 v110, v194, v110, vcc
	v_cmp_le_i32_e32 vcc, v3, v197
	v_subrev_u32_e32 v3, 36, v0
	v_add_u32_e32 v0, -4, v0
	v_cndmask_b32_e32 v126, v194, v126, vcc
	v_cmp_le_i32_e32 vcc, v3, v197
	s_nop 1
	v_cndmask_b32_e32 v111, v194, v111, vcc
	v_cmp_le_i32_e32 vcc, v0, v197
	s_nop 1
	v_cndmask_b32_e32 v127, v194, v127, vcc
.Lmaskdone_p0:
	s_nop 6
	v_max_f32_e32 v0, v96, v97
	v_max3_f32 v3, v98, v99, v113
	v_max3_f32 v0, v0, v112, v114
	v_max3_f32 v0, v0, v115, v100
	v_max3_f32 v3, v3, v102, v103
	v_max3_f32 v0, v0, v101, v116
	v_max3_f32 v3, v3, v118, v119
	v_max3_f32 v0, v0, v117, v104
	v_max3_f32 v3, v3, v106, v107
	v_max3_f32 v0, v0, v105, v120
	v_max3_f32 v3, v3, v122, v123
	v_max3_f32 v0, v0, v121, v108
	v_max3_f32 v3, v3, v110, v111
	v_max3_f32 v0, v0, v109, v124
	v_max3_f32 v3, v3, v126, v127
	v_max3_f32 v0, v0, v125, v3
	v_mov_b32_e32 v3, v0
	s_nop 1
	v_permlane32_swap_b32_e32 v0, v3
	v_max_f32_e32 v0, v0, v3
	s_cmp_lg_u32 s75, 63
	s_cselect_b64 s[60:61], -1, 0
	s_cmp_eq_u32 s75, 63
	s_mov_b64 s[62:63], -1
	s_cbranch_scc1 .LBB0_2161_p0
	v_cmp_lt_f32_e32 vcc, s31, v0
	s_cbranch_vccz .LBB0_2170_p0
	v_max_f32_e32 v0, v0, v0
	v_max_f32_e32 v0, 0, v0

; #define ATT_BAR() asm volatile("s_waitcnt lgkmcnt(0)\n\ts_barrier" ::: "memory")
; #define ATT_BAR() asm volatile("s_waitcnt vmcnt(0) lgkmcnt(0)\n\ts_barrier" ::: "memory")
; template <int DQK>
; __device__ __forceinline__ void attn_pass4(LAS unsigned char* lds, const bf16* Qp, int qpitch, const bf16* Kp, int kpitch, const bf16* Vp, int vpitch, int q0, f32x16 (&o)[4], float (&rl)[16]) {
;     ...
;         for (int t = 0; t < NT; ++t) {
;             const int vnext = ATT_VNEXT(vcur);
;             if (t + 1 < NT) ATT_DMA(t + 1, (t + 1) & 1, vnext);
;             if (ATT_VIS(t)) { ATT_A(t); ATT_B(vcur); }
;             vcur = vnext;
;             ATT_BAR();
.LBB0_2167_p0:
.LBB0_2170_p0:
	s_branch .Lend_p0
.Lnovis_p0:
.Lend_p0:
	s_add_i32 s75, s75, 64
	s_add_u32 s58, s58, 0x20000
	s_addc_u32 s59, s59, 0
	s_add_u32 s56, s56, 0x30000
	s_waitcnt vmcnt(0) lgkmcnt(0)
	s_barrier
	s_addc_u32 s57, s57, 0
	s_cmp_eq_u32 s69, s77
	s_mov_b32 s93, s78
	s_mov_b32 s78, s76
	s_mov_b32 s60, s77

.Lskip_v2_2_ba:
.LBB0_2155_ba:
	s_sub_i32 s61, s75, 63
	s_cmp_gt_i32 s61, s25
	s_cbranch_scc1 .Lnovis_ba
	s_bitcmp1_b32 s60, 0
	s_cselect_b32 s60, 0x6400, 0
	v_add_u32_e32 v0, s60, v200
	s_setprio 1
	ds_read_b128 v[238:241], v0
	ds_read_b128 v[244:247], v0 offset:32
	ds_read_b128 v[248:251], v0 offset:12800
	ds_read_b128 v[8:11], v0 offset:12832
	ds_read_b128 v[12:15], v0 offset:64
	s_waitcnt lgkmcnt(4)
	v_mfma_f32_32x32x16_bf16 v[206:221], v[238:241], v[128:131], v[80:95]
	ds_read_b128 v[238:241], v0 offset:12864
	v_exp_f32_e32 v96, v96
	v_exp_f32_e32 v97, v97
	v_exp_f32_e32 v98, v98
	v_exp_f32_e32 v99, v99
	s_waitcnt lgkmcnt(4)
	v_mfma_f32_32x32x16_bf16 v[206:221], v[244:247], v[132:135], v[206:221]
	ds_read_b128 v[244:247], v0 offset:96
	v_exp_f32_e32 v100, v100
	v_exp_f32_e32 v101, v101
	v_exp_f32_e32 v102, v102
	s_waitcnt lgkmcnt(4)
	v_mfma_f32_32x32x16_bf16 v[222:237], v[248:251], v[128:131], v[80:95]
	ds_read_b128 v[248:251], v0 offset:12896
	v_exp_f32_e32 v103, v103
	v_exp_f32_e32 v104, v104
	v_exp_f32_e32 v105, v105
	s_waitcnt lgkmcnt(4)
	v_mfma_f32_32x32x16_bf16 v[222:237], v[8:11], v[132:135], v[222:237]
	ds_read_b128 v[8:11], v0 offset:128
	v_exp_f32_e32 v106, v106
	v_exp_f32_e32 v107, v107
	v_exp_f32_e32 v108, v108
	v_exp_f32_e32 v109, v109
	s_waitcnt lgkmcnt(4)
	v_mfma_f32_32x32x16_bf16 v[206:221], v[12:15], v[136:139], v[206:221]
	ds_read_b128 v[12:15], v0 offset:12928
	v_exp_f32_e32 v110, v110
	v_exp_f32_e32 v111, v111
	v_add_f32_e32 v252, v96, v97
	s_waitcnt lgkmcnt(4)
	v_mfma_f32_32x32x16_bf16 v[222:237], v[238:241], v[136:139], v[222:237]
	ds_read_b128 v[238:241], v0 offset:160
	v_add_f32_e32 v253, v98, v99
	v_add_f32_e32 v254, v100, v101
	v_add_f32_e32 v205, v102, v103
	s_waitcnt lgkmcnt(4)
	v_mfma_f32_32x32x16_bf16 v[206:221], v[244:247], v[140:143], v[206:221]
	ds_read_b128 v[244:247], v0 offset:12960
	v_cvt_pk_bf16_f32 v96, v96, v97
	v_cvt_pk_bf16_f32 v97, v98, v99
	v_cvt_pk_bf16_f32 v98, v100, v101
	v_cvt_pk_bf16_f32 v99, v102, v103
	s_waitcnt lgkmcnt(4)
	v_mfma_f32_32x32x16_bf16 v[222:237], v[248:251], v[140:143], v[222:237]
	ds_read_b128 v[248:251], v0 offset:192
	v_exp_f32_e32 v112, v112
	v_exp_f32_e32 v113, v113
	v_exp_f32_e32 v114, v114
	s_waitcnt lgkmcnt(4)
	v_mfma_f32_32x32x16_bf16 v[206:221], v[8:11], v[144:147], v[206:221]
	ds_read_b128 v[8:11], v0 offset:12992
	v_exp_f32_e32 v115, v115
	v_exp_f32_e32 v116, v116
	v_exp_f32_e32 v117, v117
	s_waitcnt lgkmcnt(4)
	v_mfma_f32_32x32x16_bf16 v[222:237], v[12:15], v[144:147], v[222:237]
	ds_read_b128 v[12:15], v0 offset:224
	v_exp_f32_e32 v118, v118
	v_exp_f32_e32 v119, v119
	v_add_f32_e32 v252, v252, v104
	v_add_f32_e32 v253, v253, v105
	s_waitcnt lgkmcnt(4)
	v_mfma_f32_32x32x16_bf16 v[206:221], v[238:241], v[148:151], v[206:221]
	ds_read_b128 v[238:241], v0 offset:13024
	v_add_f32_e32 v254, v254, v106
	v_add_f32_e32 v205, v205, v107
	v_add_f32_e32 v252, v252, v108
	s_waitcnt lgkmcnt(4)
	v_mfma_f32_32x32x16_bf16 v[222:237], v[244:247], v[148:151], v[222:237]
	ds_read_b128 v[244:247], v0 offset:256
	v_add_f32_e32 v253, v253, v109
	v_add_f32_e32 v254, v254, v110
	v_add_f32_e32 v205, v205, v111
	s_waitcnt lgkmcnt(4)
	v_mfma_f32_32x32x16_bf16 v[206:221], v[248:251], v[152:155], v[206:221]
	ds_read_b128 v[248:251], v0 offset:13056
	v_cvt_pk_bf16_f32 v104, v104, v105
	v_cvt_pk_bf16_f32 v105, v106, v107
	v_cvt_pk_bf16_f32 v106, v108, v109
	v_cvt_pk_bf16_f32 v107, v110, v111
	s_waitcnt lgkmcnt(4)
	v_mfma_f32_32x32x16_bf16 v[222:237], v[8:11], v[152:155], v[222:237]
	ds_read_b128 v[8:11], v0 offset:288
	v_exp_f32_e32 v120, v120
	v_exp_f32_e32 v121, v121
	v_exp_f32_e32 v122, v122
	s_waitcnt lgkmcnt(4)
	v_mfma_f32_32x32x16_bf16 v[206:221], v[12:15], v[156:159], v[206:221]
	ds_read_b128 v[12:15], v0 offset:13088
	v_exp_f32_e32 v123, v123
	v_exp_f32_e32 v124, v124
	v_exp_f32_e32 v125, v125
	s_waitcnt lgkmcnt(4)
	v_mfma_f32_32x32x16_bf16 v[222:237], v[238:241], v[156:159], v[222:237]
	ds_read_b128 v[238:241], v0 offset:320
	v_exp_f32_e32 v126, v126
	v_exp_f32_e32 v127, v127
	v_add_f32_e32 v252, v252, v112
	v_add_f32_e32 v253, v253, v113
	s_waitcnt lgkmcnt(4)
	v_mfma_f32_32x32x16_bf16 v[206:221], v[244:247], v[160:163], v[206:221]
	ds_read_b128 v[244:247], v0 offset:13120
	v_add_f32_e32 v254, v254, v114
	v_add_f32_e32 v205, v205, v115
	v_add_f32_e32 v252, v252, v116
	s_waitcnt lgkmcnt(4)
	v_mfma_f32_32x32x16_bf16 v[222:237], v[248:251], v[160:163], v[222:237]
	ds_read_b128 v[248:251], v0 offset:352
	v_add_f32_e32 v253, v253, v117
	v_add_f32_e32 v254, v254, v118
	v_add_f32_e32 v205, v205, v119
	s_waitcnt lgkmcnt(4)
	v_mfma_f32_32x32x16_bf16 v[206:221], v[8:11], v[164:167], v[206:221]
	ds_read_b128 v[8:11], v0 offset:13152
	v_cvt_pk_bf16_f32 v112, v112, v113
	v_cvt_pk_bf16_f32 v113, v114, v115
	v_cvt_pk_bf16_f32 v114, v116, v117
	v_cvt_pk_bf16_f32 v115, v118, v119
	s_waitcnt lgkmcnt(4)
	v_mfma_f32_32x32x16_bf16 v[222:237], v[12:15], v[164:167], v[222:237]
	v_add_f32_e32 v252, v252, v120
	v_add_f32_e32 v253, v253, v121
	v_add_f32_e32 v254, v254, v122
	s_waitcnt lgkmcnt(3)
	v_mfma_f32_32x32x16_bf16 v[206:221], v[238:241], v[168:171], v[206:221]
	v_add_f32_e32 v205, v205, v123
	v_add_f32_e32 v252, v252, v124
	v_add_f32_e32 v253, v253, v125
	s_waitcnt lgkmcnt(2)
	v_mfma_f32_32x32x16_bf16 v[222:237], v[244:247], v[168:171], v[222:237]
	v_add_f32_e32 v254, v254, v126
	v_add_f32_e32 v205, v205, v127
	v_cvt_pk_bf16_f32 v120, v120, v121
	v_cvt_pk_bf16_f32 v121, v122, v123
	s_waitcnt lgkmcnt(1)
	v_mfma_f32_32x32x16_bf16 v[206:221], v[248:251], v[172:175], v[206:221]
	v_cvt_pk_bf16_f32 v122, v124, v125
	v_cvt_pk_bf16_f32 v123, v126, v127
	v_add_f32_e32 v252, v252, v253
	s_waitcnt lgkmcnt(0)
	v_mfma_f32_32x32x16_bf16 v[222:237], v[8:11], v[172:175], v[222:237]
	v_add_f32_e32 v254, v254, v205
	v_add_f32_e32 v252, v252, v254
	v_add_f32_e32 v2, v2, v252
	s_setprio 0
	s_cmp_le_i32 s75, s68
	s_cbranch_scc1 .Lmaskdone_ba
	v_add_u32_e32 v0, s75, v201
	v_subrev_u32_e32 v4, 31, v0
	v_subrev_u32_e32 v3, 63, v0
	v_cmp_le_i32_e32 vcc, v4, v197
	s_nop 4
	v_cndmask_b32_e32 v222, v194, v222, vcc
	v_cmp_lt_i32_e32 vcc, v3, v197
	s_nop 1
	v_cndmask_b32_e32 v207, v194, v207, vcc
	v_cmp_le_i32_e32 vcc, v3, v197
	v_subrev_u32_e32 v3, 30, v0
	s_nop 0
	v_cndmask_b32_e32 v206, v194, v206, vcc
	v_cmp_le_i32_e32 vcc, v3, v197
	v_subrev_u32_e32 v3, 61, v0
	s_nop 0
	v_cndmask_b32_e32 v223, v194, v223, vcc
	v_cmp_le_i32_e32 vcc, v3, v197
	v_subrev_u32_e32 v3, 29, v0
	s_nop 0
	v_cndmask_b32_e32 v208, v194, v208, vcc
	v_cmp_le_i32_e32 vcc, v3, v197
	v_subrev_u32_e32 v3, 60, v0
	s_nop 0
	v_cndmask_b32_e32 v224, v194, v224, vcc
	v_cmp_le_i32_e32 vcc, v3, v197
	v_subrev_u32_e32 v3, 28, v0
	s_nop 0
	v_cndmask_b32_e32 v209, v194, v209, vcc
	v_cmp_le_i32_e32 vcc, v3, v197
	v_subrev_u32_e32 v3, 55, v0
	s_nop 0
	v_cndmask_b32_e32 v225, v194, v225, vcc
	v_cmp_le_i32_e32 vcc, v3, v197
	v_subrev_u32_e32 v3, 23, v0
	s_nop 0
	v_cndmask_b32_e32 v210, v194, v210, vcc
	v_cmp_le_i32_e32 vcc, v3, v197
	v_subrev_u32_e32 v3, 54, v0
	s_nop 0
	v_cndmask_b32_e32 v226, v194, v226, vcc
	v_cmp_le_i32_e32 vcc, v3, v197
	v_subrev_u32_e32 v3, 22, v0
	s_nop 0
	v_cndmask_b32_e32 v211, v194, v211, vcc
	v_cmp_le_i32_e32 vcc, v3, v197
	v_subrev_u32_e32 v3, 53, v0
	s_nop 0
	v_cndmask_b32_e32 v227, v194, v227, vcc
	v_cmp_le_i32_e32 vcc, v3, v197
	v_subrev_u32_e32 v3, 21, v0
	s_nop 0
	v_cndmask_b32_e32 v212, v194, v212, vcc
	v_cmp_le_i32_e32 vcc, v3, v197
	v_subrev_u32_e32 v3, 52, v0
	s_nop 0
	v_cndmask_b32_e32 v228, v194, v228, vcc
	v_cmp_le_i32_e32 vcc, v3, v197
	v_subrev_u32_e32 v3, 20, v0
	s_nop 0
	v_cndmask_b32_e32 v213, v194, v213, vcc
	v_cmp_le_i32_e32 vcc, v3, v197
	v_subrev_u32_e32 v3, 47, v0
	s_nop 0
	v_cndmask_b32_e32 v229, v194, v229, vcc
	v_cmp_le_i32_e32 vcc, v3, v197
	v_add_u32_e32 v3, -15, v0
	s_nop 0
	v_cndmask_b32_e32 v214, v194, v214, vcc
	v_cmp_le_i32_e32 vcc, v3, v197
	v_subrev_u32_e32 v3, 46, v0
	s_nop 0
	v_cndmask_b32_e32 v230, v194, v230, vcc
	v_cmp_le_i32_e32 vcc, v3, v197
	v_add_u32_e32 v3, -14, v0
	s_nop 0
	v_cndmask_b32_e32 v215, v194, v215, vcc
	v_cmp_le_i32_e32 vcc, v3, v197
	v_subrev_u32_e32 v3, 45, v0
	s_nop 0
	v_cndmask_b32_e32 v231, v194, v231, vcc
	v_cmp_le_i32_e32 vcc, v3, v197
	v_add_u32_e32 v3, -13, v0
	s_nop 0
	v_cndmask_b32_e32 v216, v194, v216, vcc
	v_cmp_le_i32_e32 vcc, v3, v197
	v_subrev_u32_e32 v3, 44, v0
	s_nop 0
	v_cndmask_b32_e32 v232, v194, v232, vcc
	v_cmp_le_i32_e32 vcc, v3, v197
	v_add_u32_e32 v3, -12, v0
	s_nop 0
	v_cndmask_b32_e32 v217, v194, v217, vcc
	v_cmp_le_i32_e32 vcc, v3, v197
	v_subrev_u32_e32 v3, 39, v0
	s_nop 0
	v_cndmask_b32_e32 v233, v194, v233, vcc
	v_cmp_le_i32_e32 vcc, v3, v197
	v_add_u32_e32 v3, -7, v0
	s_nop 0
	v_cndmask_b32_e32 v218, v194, v218, vcc
	v_cmp_le_i32_e32 vcc, v3, v197
	v_subrev_u32_e32 v3, 38, v0
	s_nop 0
	v_cndmask_b32_e32 v234, v194, v234, vcc
	v_cmp_le_i32_e32 vcc, v3, v197
	v_add_u32_e32 v3, -6, v0
	s_nop 0
	v_cndmask_b32_e32 v219, v194, v219, vcc
	v_cmp_le_i32_e32 vcc, v3, v197
	v_subrev_u32_e32 v3, 37, v0
	s_nop 0
	v_cndmask_b32_e32 v235, v194, v235, vcc
	v_cmp_le_i32_e32 vcc, v3, v197
	v_add_u32_e32 v3, -5, v0
	s_nop 0
	v_cndmask_b32_e32 v220, v194, v220, vcc
	v_cmp_le_i32_e32 vcc, v3, v197
	v_subrev_u32_e32 v3, 36, v0
	v_add_u32_e32 v0, -4, v0
	v_cndmask_b32_e32 v236, v194, v236, vcc
	v_cmp_le_i32_e32 vcc, v3, v197
	s_nop 1
	v_cndmask_b32_e32 v221, v194, v221, vcc
	v_cmp_le_i32_e32 vcc, v0, v197
	s_nop 1
	v_cndmask_b32_e32 v237, v194, v237, vcc
.Lmaskdone_ba:
	s_mul_i32 s94, s93, 0x5000
	v_add_u32_e32 v4, s94, v203
	v_add_u32_e32 v5, 0xc800, v4
	s_setprio 1
	ds_read_b64_tr_b16 v[238:239], v4 offset:51200
	ds_read_b64_tr_b16 v[240:241], v4 offset:53760
	ds_read_b64_tr_b16 v[244:245], v4 offset:51264
	ds_read_b64_tr_b16 v[246:247], v4 offset:53824
	ds_read_b64_tr_b16 v[248:249], v4 offset:51328
	ds_read_b64_tr_b16 v[250:251], v4 offset:53888
	ds_read_b64_tr_b16 v[8:9], v4 offset:51392
	ds_read_b64_tr_b16 v[10:11], v4 offset:53952
	ds_read_b64_tr_b16 v[12:13], v4 offset:56320
	ds_read_b64_tr_b16 v[14:15], v4 offset:58880
	s_waitcnt lgkmcnt(8)
	v_mfma_f32_32x32x16_bf16 v[64:79], v[96:99], v[238:241], v[64:79]
	ds_read_b64_tr_b16 v[238:239], v4 offset:56384
	ds_read_b64_tr_b16 v[240:241], v4 offset:58944
	s_waitcnt lgkmcnt(8)
	v_mfma_f32_32x32x16_bf16 v[48:63], v[96:99], v[244:247], v[48:63]
	ds_read_b64_tr_b16 v[244:245], v4 offset:56448
	ds_read_b64_tr_b16 v[246:247], v4 offset:59008
	s_waitcnt lgkmcnt(8)
	v_mfma_f32_32x32x16_bf16 v[32:47], v[96:99], v[248:251], v[32:47]
	ds_read_b64_tr_b16 v[248:249], v4 offset:56512
	ds_read_b64_tr_b16 v[250:251], v4 offset:59072
	s_waitcnt lgkmcnt(8)
	v_mfma_f32_32x32x16_bf16 v[16:31], v[96:99], v[8:11], v[16:31]
	ds_read_b64_tr_b16 v[8:9], v4 offset:61440
	ds_read_b64_tr_b16 v[10:11], v4 offset:64000
	v_max_f32_e32 v0, v206, v207
	v_max3_f32 v3, v208, v209, v223
	s_waitcnt lgkmcnt(8)
	v_mfma_f32_32x32x16_bf16 v[64:79], v[104:107], v[12:15], v[64:79]
	ds_read_b64_tr_b16 v[12:13], v4 offset:61504
	ds_read_b64_tr_b16 v[14:15], v4 offset:64064
	v_max3_f32 v0, v0, v222, v224
	v_max3_f32 v0, v0, v225, v210
	s_waitcnt lgkmcnt(8)
	v_mfma_f32_32x32x16_bf16 v[48:63], v[104:107], v[238:241], v[48:63]
	ds_read_b64_tr_b16 v[238:239], v4 offset:61568
	ds_read_b64_tr_b16 v[240:241], v4 offset:64128
	v_max3_f32 v3, v3, v212, v213
	s_waitcnt lgkmcnt(8)
	v_mfma_f32_32x32x16_bf16 v[32:47], v[104:107], v[244:247], v[32:47]
	ds_read_b64_tr_b16 v[244:245], v4 offset:61632
	ds_read_b64_tr_b16 v[246:247], v4 offset:64192
	v_max3_f32 v0, v0, v211, v226
	v_max3_f32 v3, v3, v228, v229
	s_waitcnt lgkmcnt(8)
	v_mfma_f32_32x32x16_bf16 v[16:31], v[104:107], v[248:251], v[16:31]
	ds_read_b64_tr_b16 v[248:249], v5 offset:15360
	ds_read_b64_tr_b16 v[250:251], v5 offset:17920
	v_max3_f32 v0, v0, v227, v214
	v_max3_f32 v3, v3, v216, v217
	s_waitcnt lgkmcnt(8)
	v_mfma_f32_32x32x16_bf16 v[64:79], v[112:115], v[8:11], v[64:79]
	ds_read_b64_tr_b16 v[8:9], v5 offset:15424
	ds_read_b64_tr_b16 v[10:11], v5 offset:17984
	v_max3_f32 v0, v0, v215, v230
	s_waitcnt lgkmcnt(8)
	v_mfma_f32_32x32x16_bf16 v[48:63], v[112:115], v[12:15], v[48:63]
	ds_read_b64_tr_b16 v[12:13], v5 offset:15488
	ds_read_b64_tr_b16 v[14:15], v5 offset:18048
	v_max3_f32 v3, v3, v232, v233
	v_max3_f32 v0, v0, v231, v218
	s_waitcnt lgkmcnt(8)
	v_mfma_f32_32x32x16_bf16 v[32:47], v[112:115], v[238:241], v[32:47]
	ds_read_b64_tr_b16 v[238:239], v5 offset:15552
	ds_read_b64_tr_b16 v[240:241], v5 offset:18112
	v_max3_f32 v3, v3, v220, v221
	v_max3_f32 v0, v0, v219, v234
	s_waitcnt lgkmcnt(8)
	v_mfma_f32_32x32x16_bf16 v[16:31], v[112:115], v[244:247], v[16:31]
	v_max3_f32 v3, v3, v236, v237
	s_waitcnt lgkmcnt(6)
	v_mfma_f32_32x32x16_bf16 v[64:79], v[120:123], v[248:251], v[64:79]
	v_max3_f32 v0, v0, v235, v3
	v_mov_b32_e32 v3, v0
	s_waitcnt lgkmcnt(4)
	v_mfma_f32_32x32x16_bf16 v[48:63], v[120:123], v[8:11], v[48:63]
	s_nop 1
	v_permlane32_swap_b32_e32 v0, v3
	s_waitcnt lgkmcnt(2)
	v_mfma_f32_32x32x16_bf16 v[32:47], v[120:123], v[12:15], v[32:47]
	v_max_f32_e32 v0, v0, v3
	s_waitcnt lgkmcnt(0)
	v_mfma_f32_32x32x16_bf16 v[16:31], v[120:123], v[238:241], v[16:31]
	s_setprio 0
	s_cmp_lg_u32 s75, 63
	s_cselect_b64 s[60:61], -1, 0
	s_cmp_eq_u32 s75, 63
	s_mov_b64 s[62:63], -1
	s_cbranch_scc1 .LBB0_2161_ba
	v_cmp_lt_f32_e32 vcc, s31, v0
	s_cbranch_vccz .LBB0_2170_ba
	v_max_f32_e32 v0, v0, v0
	v_max_f32_e32 v0, 0, v0

.LBB0_2166_ba:
	v_add_f32_e32 v204, v204, v0
	v_xor_b32_e32 v80, 0x80000000, v204
	v_sub_f32_e32 v221, v221, v0
	v_sub_f32_e32 v220, v220, v0
	v_sub_f32_e32 v219, v219, v0
	v_sub_f32_e32 v218, v218, v0
	v_sub_f32_e32 v217, v217, v0
	v_sub_f32_e32 v216, v216, v0
	v_sub_f32_e32 v215, v215, v0
	v_sub_f32_e32 v214, v214, v0
	v_sub_f32_e32 v213, v213, v0
	v_sub_f32_e32 v212, v212, v0
	v_sub_f32_e32 v211, v211, v0
	v_sub_f32_e32 v210, v210, v0
	v_sub_f32_e32 v209, v209, v0
	v_sub_f32_e32 v208, v208, v0
	v_sub_f32_e32 v207, v207, v0
	v_sub_f32_e32 v206, v206, v0
	v_sub_f32_e32 v237, v237, v0
	v_sub_f32_e32 v236, v236, v0
	v_sub_f32_e32 v235, v235, v0
	v_sub_f32_e32 v234, v234, v0
	v_sub_f32_e32 v233, v233, v0
	v_sub_f32_e32 v232, v232, v0
	v_sub_f32_e32 v231, v231, v0
	v_sub_f32_e32 v230, v230, v0
	v_sub_f32_e32 v229, v229, v0
	v_sub_f32_e32 v228, v228, v0
	v_sub_f32_e32 v227, v227, v0
	v_sub_f32_e32 v226, v226, v0
	v_sub_f32_e32 v225, v225, v0
	v_sub_f32_e32 v224, v224, v0
	v_sub_f32_e32 v223, v223, v0
	v_sub_f32_e32 v222, v222, v0
	v_mov_b32_e32 v81, v80
	v_mov_b32_e32 v82, v80
	v_mov_b32_e32 v83, v80
	v_mov_b32_e32 v84, v80
	v_mov_b32_e32 v85, v80
	v_mov_b32_e32 v86, v80
	v_mov_b32_e32 v87, v80
	v_mov_b32_e32 v88, v80
	v_mov_b32_e32 v89, v80
	v_mov_b32_e32 v90, v80
	v_mov_b32_e32 v91, v80
	v_mov_b32_e32 v92, v80
	v_mov_b32_e32 v93, v80
	v_mov_b32_e32 v94, v80
	v_mov_b32_e32 v95, v80

; #define ATT_BAR() asm volatile("s_waitcnt lgkmcnt(0)\n\ts_barrier" ::: "memory")
; #define ATT_BAR() asm volatile("s_waitcnt vmcnt(0) lgkmcnt(0)\n\ts_barrier" ::: "memory")
; template <int DQK>
; __device__ __forceinline__ void attn_pass4(LAS unsigned char* lds, const bf16* Qp, int qpitch, const bf16* Kp, int kpitch, const bf16* Vp, int vpitch, int q0, f32x16 (&o)[4], float (&rl)[16]) {
;     ...
;         for (int t = 0; t < NT; ++t) {
;             const int vnext = ATT_VNEXT(vcur);
;             if (t + 1 < NT) ATT_DMA(t + 1, (t + 1) & 1, vnext);
;             if (ATT_VIS(t)) { ATT_A(t); ATT_B(vcur); }
;             vcur = vnext;
;             ATT_BAR();
.Lnovis_ba:
	s_sub_i32 s61, s75, 0x7f
	s_cmp_gt_i32 s61, s25
	s_cbranch_scc1 .Lend_ba
	s_mul_i32 s94, s93, 0x5000
	v_add_u32_e32 v4, s94, v203
	v_add_u32_e32 v5, 0xc800, v4
	s_setprio 1
	ds_read_b64_tr_b16 v[238:239], v4 offset:51200
	ds_read_b64_tr_b16 v[240:241], v4 offset:53760
	ds_read_b64_tr_b16 v[244:245], v4 offset:51264
	ds_read_b64_tr_b16 v[246:247], v4 offset:53824
	ds_read_b64_tr_b16 v[248:249], v4 offset:51328
	ds_read_b64_tr_b16 v[250:251], v4 offset:53888
	ds_read_b64_tr_b16 v[8:9], v4 offset:51392
	ds_read_b64_tr_b16 v[10:11], v4 offset:53952
	ds_read_b64_tr_b16 v[12:13], v4 offset:56320
	ds_read_b64_tr_b16 v[14:15], v4 offset:58880
	v_exp_f32_e32 v96, v96
	v_exp_f32_e32 v97, v97
	v_exp_f32_e32 v98, v98
	v_exp_f32_e32 v99, v99
	v_exp_f32_e32 v100, v100
	v_exp_f32_e32 v101, v101
	v_exp_f32_e32 v102, v102
	v_exp_f32_e32 v103, v103
	v_add_f32_e32 v252, v96, v97
	v_add_f32_e32 v253, v98, v99
	v_add_f32_e32 v254, v100, v101
	v_add_f32_e32 v205, v102, v103
	s_nop 0
	v_cvt_pk_bf16_f32 v96, v96, v97
	v_cvt_pk_bf16_f32 v97, v98, v99
	v_cvt_pk_bf16_f32 v98, v100, v101
	v_cvt_pk_bf16_f32 v99, v102, v103
	s_nop 1
	s_waitcnt lgkmcnt(8)
	v_mfma_f32_32x32x16_bf16 v[64:79], v[96:99], v[238:241], v[64:79]
	ds_read_b64_tr_b16 v[238:239], v4 offset:56384
	ds_read_b64_tr_b16 v[240:241], v4 offset:58944
	v_exp_f32_e32 v104, v104
	v_exp_f32_e32 v105, v105
	v_exp_f32_e32 v106, v106
	v_exp_f32_e32 v107, v107
	v_exp_f32_e32 v108, v108
	v_exp_f32_e32 v109, v109
	s_waitcnt lgkmcnt(8)
	v_mfma_f32_32x32x16_bf16 v[48:63], v[96:99], v[244:247], v[48:63]
	ds_read_b64_tr_b16 v[244:245], v4 offset:56448
	ds_read_b64_tr_b16 v[246:247], v4 offset:59008
	v_exp_f32_e32 v110, v110
	v_exp_f32_e32 v111, v111
	v_add_f32_e32 v252, v252, v104
	v_add_f32_e32 v253, v253, v105
	v_add_f32_e32 v254, v254, v106
	s_waitcnt lgkmcnt(8)
	v_mfma_f32_32x32x16_bf16 v[32:47], v[96:99], v[248:251], v[32:47]
	ds_read_b64_tr_b16 v[248:249], v4 offset:56512
	ds_read_b64_tr_b16 v[250:251], v4 offset:59072
	v_add_f32_e32 v205, v205, v107
	v_add_f32_e32 v252, v252, v108
	v_add_f32_e32 v253, v253, v109
	v_add_f32_e32 v254, v254, v110
	v_add_f32_e32 v205, v205, v111
	s_waitcnt lgkmcnt(8)
	v_mfma_f32_32x32x16_bf16 v[16:31], v[96:99], v[8:11], v[16:31]
	ds_read_b64_tr_b16 v[8:9], v4 offset:61440
	ds_read_b64_tr_b16 v[10:11], v4 offset:64000
	v_cvt_pk_bf16_f32 v104, v104, v105
	v_cvt_pk_bf16_f32 v105, v106, v107
	v_cvt_pk_bf16_f32 v106, v108, v109
	v_cvt_pk_bf16_f32 v107, v110, v111
	s_nop 1
	s_waitcnt lgkmcnt(8)
	v_mfma_f32_32x32x16_bf16 v[64:79], v[104:107], v[12:15], v[64:79]
	ds_read_b64_tr_b16 v[12:13], v4 offset:61504
	ds_read_b64_tr_b16 v[14:15], v4 offset:64064
	v_exp_f32_e32 v112, v112
	v_exp_f32_e32 v113, v113
	v_exp_f32_e32 v114, v114
	v_exp_f32_e32 v115, v115
	v_exp_f32_e32 v116, v116
	v_exp_f32_e32 v117, v117
	s_waitcnt lgkmcnt(8)
	v_mfma_f32_32x32x16_bf16 v[48:63], v[104:107], v[238:241], v[48:63]
	ds_read_b64_tr_b16 v[238:239], v4 offset:61568
	ds_read_b64_tr_b16 v[240:241], v4 offset:64128
	v_exp_f32_e32 v118, v118
	v_exp_f32_e32 v119, v119
	v_add_f32_e32 v252, v252, v112
	v_add_f32_e32 v253, v253, v113
	v_add_f32_e32 v254, v254, v114
	s_waitcnt lgkmcnt(8)
	v_mfma_f32_32x32x16_bf16 v[32:47], v[104:107], v[244:247], v[32:47]
	ds_read_b64_tr_b16 v[244:245], v4 offset:61632
	ds_read_b64_tr_b16 v[246:247], v4 offset:64192
	v_add_f32_e32 v205, v205, v115
	v_add_f32_e32 v252, v252, v116
	v_add_f32_e32 v253, v253, v117
	v_add_f32_e32 v254, v254, v118
	v_add_f32_e32 v205, v205, v119
	s_waitcnt lgkmcnt(8)
	v_mfma_f32_32x32x16_bf16 v[16:31], v[104:107], v[248:251], v[16:31]
	ds_read_b64_tr_b16 v[248:249], v5 offset:15360
	ds_read_b64_tr_b16 v[250:251], v5 offset:17920
	v_cvt_pk_bf16_f32 v112, v112, v113
	v_cvt_pk_bf16_f32 v113, v114, v115
	v_cvt_pk_bf16_f32 v114, v116, v117
	v_cvt_pk_bf16_f32 v115, v118, v119
	s_nop 1
	s_waitcnt lgkmcnt(8)
	v_mfma_f32_32x32x16_bf16 v[64:79], v[112:115], v[8:11], v[64:79]
	ds_read_b64_tr_b16 v[8:9], v5 offset:15424
	ds_read_b64_tr_b16 v[10:11], v5 offset:17984
	v_exp_f32_e32 v120, v120
	v_exp_f32_e32 v121, v121
	v_exp_f32_e32 v122, v122
	v_exp_f32_e32 v123, v123
	v_exp_f32_e32 v124, v124
	v_exp_f32_e32 v125, v125
	s_waitcnt lgkmcnt(8)
	v_mfma_f32_32x32x16_bf16 v[48:63], v[112:115], v[12:15], v[48:63]
	ds_read_b64_tr_b16 v[12:13], v5 offset:15488
	ds_read_b64_tr_b16 v[14:15], v5 offset:18048
	v_exp_f32_e32 v126, v126
	v_exp_f32_e32 v127, v127
	v_add_f32_e32 v252, v252, v120
	v_add_f32_e32 v253, v253, v121
	v_add_f32_e32 v254, v254, v122
	s_waitcnt lgkmcnt(8)
	v_mfma_f32_32x32x16_bf16 v[32:47], v[112:115], v[238:241], v[32:47]
	ds_read_b64_tr_b16 v[238:239], v5 offset:15552
	ds_read_b64_tr_b16 v[240:241], v5 offset:18112
	v_add_f32_e32 v205, v205, v123
	v_add_f32_e32 v252, v252, v124
	v_add_f32_e32 v253, v253, v125
	v_add_f32_e32 v254, v254, v126
	v_add_f32_e32 v205, v205, v127
	s_waitcnt lgkmcnt(8)
	v_mfma_f32_32x32x16_bf16 v[16:31], v[112:115], v[244:247], v[16:31]
	v_cvt_pk_bf16_f32 v120, v120, v121
	v_cvt_pk_bf16_f32 v121, v122, v123
	v_cvt_pk_bf16_f32 v122, v124, v125
	v_cvt_pk_bf16_f32 v123, v126, v127
	s_nop 1
	s_waitcnt lgkmcnt(6)
	v_mfma_f32_32x32x16_bf16 v[64:79], v[120:123], v[248:251], v[64:79]
	v_add_f32_e32 v252, v252, v253
	s_waitcnt lgkmcnt(4)
	v_mfma_f32_32x32x16_bf16 v[48:63], v[120:123], v[8:11], v[48:63]
	v_add_f32_e32 v254, v254, v205
	s_waitcnt lgkmcnt(2)
	v_mfma_f32_32x32x16_bf16 v[32:47], v[120:123], v[12:15], v[32:47]
	v_add_f32_e32 v252, v252, v254
	s_waitcnt lgkmcnt(0)
	v_mfma_f32_32x32x16_bf16 v[16:31], v[120:123], v[238:241], v[16:31]
	v_add_f32_e32 v2, v2, v252
	s_setprio 0
.Lend_ba:
	s_add_i32 s75, s75, 64
	s_add_u32 s58, s58, 0x20000
	s_addc_u32 s59, s59, 0
	s_add_u32 s56, s56, 0x30000
	s_waitcnt vmcnt(0) lgkmcnt(0)
	s_barrier
	s_addc_u32 s57, s57, 0
	s_cmp_eq_u32 s69, s77
	s_mov_b32 s93, s78
	s_mov_b32 s78, s76
	s_mov_b32 s60, s77
	s_add_i32 s61, s78, 1
	s_cmp_lg_u32 s78, 2
	s_cselect_b32 s76, s61, 0
	s_add_i32 s77, s60, 1
	s_cmp_ge_u32 s77, s69
	s_cbranch_scc1 .LBB0_2155_ab
	s_bitcmp1_b32 s77, 0
	s_cselect_b32 s61, 0x6400, 0
	s_add_i32 s62, s61, s2
	s_add_i32 s62, s62, 0

	s_mov_b32 s63, m0
	s_mov_b32 m0, s62
	s_nop 0
	global_load_lds_dwordx4 v180, s[56:57]
	s_mov_b32 m0, s63
	s_add_i32 s62, s61, s72
	s_add_i32 s62, s62, 0

	s_mov_b32 s63, m0
	s_mov_b32 m0, s62
	s_nop 0
	global_load_lds_dwordx4 v182, s[56:57]
	s_mov_b32 m0, s63
	s_add_i32 s62, s61, s73

	s_add_i32 s62, s62, 0
	s_mov_b32 s63, m0
	s_mov_b32 m0, s62
	s_nop 0
	global_load_lds_dwordx4 v184, s[56:57]
	s_mov_b32 m0, s63
	s_andn2_b64 vcc, exec, s[12:13]
	s_cbranch_vccnz .LBB0_2154_ab
	s_add_i32 s61, s61, s74

	s_add_i32 s61, s61, 0
	s_mov_b32 s62, m0
	s_mov_b32 m0, s61
	s_nop 0
	global_load_lds_dwordx4 v190, s[56:57]
	s_mov_b32 m0, s62

.Lskip_v2_2_ab:
.LBB0_2155_ab:
	s_sub_i32 s61, s75, 63
	s_cmp_gt_i32 s61, s25
	s_cbranch_scc1 .Lnovis_ab
	s_bitcmp1_b32 s60, 0
	s_cselect_b32 s60, 0x6400, 0
	v_add_u32_e32 v0, s60, v200
	s_setprio 1
	ds_read_b128 v[238:241], v0
	ds_read_b128 v[244:247], v0 offset:32
	ds_read_b128 v[248:251], v0 offset:12800
	ds_read_b128 v[8:11], v0 offset:12832
	ds_read_b128 v[12:15], v0 offset:64
	s_waitcnt lgkmcnt(4)
	v_mfma_f32_32x32x16_bf16 v[96:111], v[238:241], v[128:131], v[80:95]
	ds_read_b128 v[238:241], v0 offset:12864
	v_exp_f32_e32 v206, v206
	v_exp_f32_e32 v207, v207
	v_exp_f32_e32 v208, v208
	v_exp_f32_e32 v209, v209
	s_waitcnt lgkmcnt(4)
	v_mfma_f32_32x32x16_bf16 v[96:111], v[244:247], v[132:135], v[96:111]
	ds_read_b128 v[244:247], v0 offset:96
	v_exp_f32_e32 v210, v210
	v_exp_f32_e32 v211, v211
	v_exp_f32_e32 v212, v212
	s_waitcnt lgkmcnt(4)
	v_mfma_f32_32x32x16_bf16 v[112:127], v[248:251], v[128:131], v[80:95]
	ds_read_b128 v[248:251], v0 offset:12896
	v_exp_f32_e32 v213, v213
	v_exp_f32_e32 v214, v214
	v_exp_f32_e32 v215, v215
	s_waitcnt lgkmcnt(4)
	v_mfma_f32_32x32x16_bf16 v[112:127], v[8:11], v[132:135], v[112:127]
	ds_read_b128 v[8:11], v0 offset:128
	v_exp_f32_e32 v216, v216
	v_exp_f32_e32 v217, v217
	v_exp_f32_e32 v218, v218
	v_exp_f32_e32 v219, v219
	s_waitcnt lgkmcnt(4)
	v_mfma_f32_32x32x16_bf16 v[96:111], v[12:15], v[136:139], v[96:111]
	ds_read_b128 v[12:15], v0 offset:12928
	v_exp_f32_e32 v220, v220
	v_exp_f32_e32 v221, v221
	v_add_f32_e32 v252, v206, v207
	s_waitcnt lgkmcnt(4)
	v_mfma_f32_32x32x16_bf16 v[112:127], v[238:241], v[136:139], v[112:127]
	ds_read_b128 v[238:241], v0 offset:160
	v_add_f32_e32 v253, v208, v209
	v_add_f32_e32 v254, v210, v211
	v_add_f32_e32 v205, v212, v213
	s_waitcnt lgkmcnt(4)
	v_mfma_f32_32x32x16_bf16 v[96:111], v[244:247], v[140:143], v[96:111]
	ds_read_b128 v[244:247], v0 offset:12960
	v_cvt_pk_bf16_f32 v206, v206, v207
	v_cvt_pk_bf16_f32 v207, v208, v209
	v_cvt_pk_bf16_f32 v208, v210, v211
	v_cvt_pk_bf16_f32 v209, v212, v213
	s_waitcnt lgkmcnt(4)
	v_mfma_f32_32x32x16_bf16 v[112:127], v[248:251], v[140:143], v[112:127]
	ds_read_b128 v[248:251], v0 offset:192
	v_exp_f32_e32 v222, v222
	v_exp_f32_e32 v223, v223
	v_exp_f32_e32 v224, v224
	s_waitcnt lgkmcnt(4)
	v_mfma_f32_32x32x16_bf16 v[96:111], v[8:11], v[144:147], v[96:111]
	ds_read_b128 v[8:11], v0 offset:12992
	v_exp_f32_e32 v225, v225
	v_exp_f32_e32 v226, v226
	v_exp_f32_e32 v227, v227
	s_waitcnt lgkmcnt(4)
	v_mfma_f32_32x32x16_bf16 v[112:127], v[12:15], v[144:147], v[112:127]
	ds_read_b128 v[12:15], v0 offset:224
	v_exp_f32_e32 v228, v228
	v_exp_f32_e32 v229, v229
	v_add_f32_e32 v252, v252, v214
	v_add_f32_e32 v253, v253, v215
	s_waitcnt lgkmcnt(4)
	v_mfma_f32_32x32x16_bf16 v[96:111], v[238:241], v[148:151], v[96:111]
	ds_read_b128 v[238:241], v0 offset:13024
	v_add_f32_e32 v254, v254, v216
	v_add_f32_e32 v205, v205, v217
	v_add_f32_e32 v252, v252, v218
	s_waitcnt lgkmcnt(4)
	v_mfma_f32_32x32x16_bf16 v[112:127], v[244:247], v[148:151], v[112:127]
	ds_read_b128 v[244:247], v0 offset:256
	v_add_f32_e32 v253, v253, v219
	v_add_f32_e32 v254, v254, v220
	v_add_f32_e32 v205, v205, v221
	s_waitcnt lgkmcnt(4)
	v_mfma_f32_32x32x16_bf16 v[96:111], v[248:251], v[152:155], v[96:111]
	ds_read_b128 v[248:251], v0 offset:13056
	v_cvt_pk_bf16_f32 v214, v214, v215
	v_cvt_pk_bf16_f32 v215, v216, v217
	v_cvt_pk_bf16_f32 v216, v218, v219
	v_cvt_pk_bf16_f32 v217, v220, v221
	s_waitcnt lgkmcnt(4)
	v_mfma_f32_32x32x16_bf16 v[112:127], v[8:11], v[152:155], v[112:127]
	ds_read_b128 v[8:11], v0 offset:288
	v_exp_f32_e32 v230, v230
	v_exp_f32_e32 v231, v231
	v_exp_f32_e32 v232, v232
	s_waitcnt lgkmcnt(4)
	v_mfma_f32_32x32x16_bf16 v[96:111], v[12:15], v[156:159], v[96:111]
	ds_read_b128 v[12:15], v0 offset:13088
	v_exp_f32_e32 v233, v233
	v_exp_f32_e32 v234, v234
	v_exp_f32_e32 v235, v235
	s_waitcnt lgkmcnt(4)
	v_mfma_f32_32x32x16_bf16 v[112:127], v[238:241], v[156:159], v[112:127]
	ds_read_b128 v[238:241], v0 offset:320
	v_exp_f32_e32 v236, v236
	v_exp_f32_e32 v237, v237
	v_add_f32_e32 v252, v252, v222
	v_add_f32_e32 v253, v253, v223
	s_waitcnt lgkmcnt(4)
	v_mfma_f32_32x32x16_bf16 v[96:111], v[244:247], v[160:163], v[96:111]
	ds_read_b128 v[244:247], v0 offset:13120
	v_add_f32_e32 v254, v254, v224
	v_add_f32_e32 v205, v205, v225
	v_add_f32_e32 v252, v252, v226
	s_waitcnt lgkmcnt(4)
	v_mfma_f32_32x32x16_bf16 v[112:127], v[248:251], v[160:163], v[112:127]
	ds_read_b128 v[248:251], v0 offset:352
	v_add_f32_e32 v253, v253, v227
	v_add_f32_e32 v254, v254, v228
	v_add_f32_e32 v205, v205, v229
	s_waitcnt lgkmcnt(4)
	v_mfma_f32_32x32x16_bf16 v[96:111], v[8:11], v[164:167], v[96:111]
	ds_read_b128 v[8:11], v0 offset:13152
	v_cvt_pk_bf16_f32 v222, v222, v223
	v_cvt_pk_bf16_f32 v223, v224, v225
	v_cvt_pk_bf16_f32 v224, v226, v227
	v_cvt_pk_bf16_f32 v225, v228, v229
	s_waitcnt lgkmcnt(4)
	v_mfma_f32_32x32x16_bf16 v[112:127], v[12:15], v[164:167], v[112:127]
	v_add_f32_e32 v252, v252, v230
	v_add_f32_e32 v253, v253, v231
	v_add_f32_e32 v254, v254, v232
	s_waitcnt lgkmcnt(3)
	v_mfma_f32_32x32x16_bf16 v[96:111], v[238:241], v[168:171], v[96:111]
	v_add_f32_e32 v205, v205, v233
	v_add_f32_e32 v252, v252, v234
	v_add_f32_e32 v253, v253, v235
	s_waitcnt lgkmcnt(2)
	v_mfma_f32_32x32x16_bf16 v[112:127], v[244:247], v[168:171], v[112:127]
	v_add_f32_e32 v254, v254, v236
	v_add_f32_e32 v205, v205, v237
	v_cvt_pk_bf16_f32 v230, v230, v231
	v_cvt_pk_bf16_f32 v231, v232, v233
	s_waitcnt lgkmcnt(1)
	v_mfma_f32_32x32x16_bf16 v[96:111], v[248:251], v[172:175], v[96:111]
	v_cvt_pk_bf16_f32 v232, v234, v235
	v_cvt_pk_bf16_f32 v233, v236, v237
	v_add_f32_e32 v252, v252, v253
	s_waitcnt lgkmcnt(0)
	v_mfma_f32_32x32x16_bf16 v[112:127], v[8:11], v[172:175], v[112:127]
	v_add_f32_e32 v254, v254, v205
	v_add_f32_e32 v252, v252, v254
	v_add_f32_e32 v2, v2, v252
	s_setprio 0
	s_cmp_le_i32 s75, s68
	s_cbranch_scc1 .Lmaskdone_ab
	v_add_u32_e32 v0, s75, v201
	v_subrev_u32_e32 v4, 31, v0
	v_subrev_u32_e32 v3, 63, v0
	v_cmp_le_i32_e32 vcc, v4, v197
	s_nop 4
	v_cndmask_b32_e32 v112, v194, v112, vcc
	v_cmp_lt_i32_e32 vcc, v3, v197
	s_nop 1
	v_cndmask_b32_e32 v97, v194, v97, vcc
	v_cmp_le_i32_e32 vcc, v3, v197
	v_subrev_u32_e32 v3, 30, v0
	s_nop 0
	v_cndmask_b32_e32 v96, v194, v96, vcc
	v_cmp_le_i32_e32 vcc, v3, v197
	v_subrev_u32_e32 v3, 61, v0
	s_nop 0
	v_cndmask_b32_e32 v113, v194, v113, vcc
	v_cmp_le_i32_e32 vcc, v3, v197
	v_subrev_u32_e32 v3, 29, v0
	s_nop 0
	v_cndmask_b32_e32 v98, v194, v98, vcc
	v_cmp_le_i32_e32 vcc, v3, v197
	v_subrev_u32_e32 v3, 60, v0
	s_nop 0
	v_cndmask_b32_e32 v114, v194, v114, vcc
	v_cmp_le_i32_e32 vcc, v3, v197
	v_subrev_u32_e32 v3, 28, v0
	s_nop 0
	v_cndmask_b32_e32 v99, v194, v99, vcc
	v_cmp_le_i32_e32 vcc, v3, v197
	v_subrev_u32_e32 v3, 55, v0
	s_nop 0
	v_cndmask_b32_e32 v115, v194, v115, vcc
	v_cmp_le_i32_e32 vcc, v3, v197
	v_subrev_u32_e32 v3, 23, v0
	s_nop 0
	v_cndmask_b32_e32 v100, v194, v100, vcc
	v_cmp_le_i32_e32 vcc, v3, v197
	v_subrev_u32_e32 v3, 54, v0
	s_nop 0
	v_cndmask_b32_e32 v116, v194, v116, vcc
	v_cmp_le_i32_e32 vcc, v3, v197
	v_subrev_u32_e32 v3, 22, v0
	s_nop 0
	v_cndmask_b32_e32 v101, v194, v101, vcc
	v_cmp_le_i32_e32 vcc, v3, v197
	v_subrev_u32_e32 v3, 53, v0
	s_nop 0
	v_cndmask_b32_e32 v117, v194, v117, vcc
	v_cmp_le_i32_e32 vcc, v3, v197
	v_subrev_u32_e32 v3, 21, v0
	s_nop 0
	v_cndmask_b32_e32 v102, v194, v102, vcc
	v_cmp_le_i32_e32 vcc, v3, v197
	v_subrev_u32_e32 v3, 52, v0
	s_nop 0
	v_cndmask_b32_e32 v118, v194, v118, vcc
	v_cmp_le_i32_e32 vcc, v3, v197
	v_subrev_u32_e32 v3, 20, v0
	s_nop 0
	v_cndmask_b32_e32 v103, v194, v103, vcc
	v_cmp_le_i32_e32 vcc, v3, v197
	v_subrev_u32_e32 v3, 47, v0
	s_nop 0
	v_cndmask_b32_e32 v119, v194, v119, vcc
	v_cmp_le_i32_e32 vcc, v3, v197
	v_add_u32_e32 v3, -15, v0
	s_nop 0
	v_cndmask_b32_e32 v104, v194, v104, vcc
	v_cmp_le_i32_e32 vcc, v3, v197
	v_subrev_u32_e32 v3, 46, v0
	s_nop 0
	v_cndmask_b32_e32 v120, v194, v120, vcc
	v_cmp_le_i32_e32 vcc, v3, v197
	v_add_u32_e32 v3, -14, v0
	s_nop 0
	v_cndmask_b32_e32 v105, v194, v105, vcc
	v_cmp_le_i32_e32 vcc, v3, v197
	v_subrev_u32_e32 v3, 45, v0
	s_nop 0
	v_cndmask_b32_e32 v121, v194, v121, vcc
	v_cmp_le_i32_e32 vcc, v3, v197
	v_add_u32_e32 v3, -13, v0
	s_nop 0
	v_cndmask_b32_e32 v106, v194, v106, vcc
	v_cmp_le_i32_e32 vcc, v3, v197
	v_subrev_u32_e32 v3, 44, v0
	s_nop 0
	v_cndmask_b32_e32 v122, v194, v122, vcc
	v_cmp_le_i32_e32 vcc, v3, v197
	v_add_u32_e32 v3, -12, v0
	s_nop 0
	v_cndmask_b32_e32 v107, v194, v107, vcc
	v_cmp_le_i32_e32 vcc, v3, v197
	v_subrev_u32_e32 v3, 39, v0
	s_nop 0
	v_cndmask_b32_e32 v123, v194, v123, vcc
	v_cmp_le_i32_e32 vcc, v3, v197
	v_add_u32_e32 v3, -7, v0
	s_nop 0
	v_cndmask_b32_e32 v108, v194, v108, vcc
	v_cmp_le_i32_e32 vcc, v3, v197
	v_subrev_u32_e32 v3, 38, v0
	s_nop 0
	v_cndmask_b32_e32 v124, v194, v124, vcc
	v_cmp_le_i32_e32 vcc, v3, v197
	v_add_u32_e32 v3, -6, v0
	s_nop 0
	v_cndmask_b32_e32 v109, v194, v109, vcc
	v_cmp_le_i32_e32 vcc, v3, v197
	v_subrev_u32_e32 v3, 37, v0
	s_nop 0
	v_cndmask_b32_e32 v125, v194, v125, vcc
	v_cmp_le_i32_e32 vcc, v3, v197
	v_add_u32_e32 v3, -5, v0
	s_nop 0
	v_cndmask_b32_e32 v110, v194, v110, vcc
	v_cmp_le_i32_e32 vcc, v3, v197
	v_subrev_u32_e32 v3, 36, v0
	v_add_u32_e32 v0, -4, v0
	v_cndmask_b32_e32 v126, v194, v126, vcc
	v_cmp_le_i32_e32 vcc, v3, v197
	s_nop 1
	v_cndmask_b32_e32 v111, v194, v111, vcc
	v_cmp_le_i32_e32 vcc, v0, v197
	s_nop 1
	v_cndmask_b32_e32 v127, v194, v127, vcc
.Lmaskdone_ab:
	s_mul_i32 s94, s93, 0x5000
	v_add_u32_e32 v4, s94, v203
	v_add_u32_e32 v5, 0xc800, v4
	s_setprio 1
	ds_read_b64_tr_b16 v[238:239], v4 offset:51200
	ds_read_b64_tr_b16 v[240:241], v4 offset:53760
	ds_read_b64_tr_b16 v[244:245], v4 offset:51264
	ds_read_b64_tr_b16 v[246:247], v4 offset:53824
	ds_read_b64_tr_b16 v[248:249], v4 offset:51328
	ds_read_b64_tr_b16 v[250:251], v4 offset:53888
	ds_read_b64_tr_b16 v[8:9], v4 offset:51392
	ds_read_b64_tr_b16 v[10:11], v4 offset:53952
	ds_read_b64_tr_b16 v[12:13], v4 offset:56320
	ds_read_b64_tr_b16 v[14:15], v4 offset:58880
	s_waitcnt lgkmcnt(8)
	v_mfma_f32_32x32x16_bf16 v[64:79], v[206:209], v[238:241], v[64:79]
	ds_read_b64_tr_b16 v[238:239], v4 offset:56384
	ds_read_b64_tr_b16 v[240:241], v4 offset:58944
	s_waitcnt lgkmcnt(8)
	v_mfma_f32_32x32x16_bf16 v[48:63], v[206:209], v[244:247], v[48:63]
	ds_read_b64_tr_b16 v[244:245], v4 offset:56448
	ds_read_b64_tr_b16 v[246:247], v4 offset:59008
	s_waitcnt lgkmcnt(8)
	v_mfma_f32_32x32x16_bf16 v[32:47], v[206:209], v[248:251], v[32:47]
	ds_read_b64_tr_b16 v[248:249], v4 offset:56512
	ds_read_b64_tr_b16 v[250:251], v4 offset:59072
	s_waitcnt lgkmcnt(8)
	v_mfma_f32_32x32x16_bf16 v[16:31], v[206:209], v[8:11], v[16:31]
	ds_read_b64_tr_b16 v[8:9], v4 offset:61440
	ds_read_b64_tr_b16 v[10:11], v4 offset:64000
	v_max_f32_e32 v0, v96, v97
	v_max3_f32 v3, v98, v99, v113
	s_waitcnt lgkmcnt(8)
	v_mfma_f32_32x32x16_bf16 v[64:79], v[214:217], v[12:15], v[64:79]
	ds_read_b64_tr_b16 v[12:13], v4 offset:61504
	ds_read_b64_tr_b16 v[14:15], v4 offset:64064
	v_max3_f32 v0, v0, v112, v114
	v_max3_f32 v0, v0, v115, v100
	s_waitcnt lgkmcnt(8)
	v_mfma_f32_32x32x16_bf16 v[48:63], v[214:217], v[238:241], v[48:63]
	ds_read_b64_tr_b16 v[238:239], v4 offset:61568
	ds_read_b64_tr_b16 v[240:241], v4 offset:64128
	v_max3_f32 v3, v3, v102, v103
	s_waitcnt lgkmcnt(8)
	v_mfma_f32_32x32x16_bf16 v[32:47], v[214:217], v[244:247], v[32:47]
	ds_read_b64_tr_b16 v[244:245], v4 offset:61632
	ds_read_b64_tr_b16 v[246:247], v4 offset:64192
	v_max3_f32 v0, v0, v101, v116
	v_max3_f32 v3, v3, v118, v119
	s_waitcnt lgkmcnt(8)
	v_mfma_f32_32x32x16_bf16 v[16:31], v[214:217], v[248:251], v[16:31]
	ds_read_b64_tr_b16 v[248:249], v5 offset:15360
	ds_read_b64_tr_b16 v[250:251], v5 offset:17920
	v_max3_f32 v0, v0, v117, v104
	v_max3_f32 v3, v3, v106, v107
	s_waitcnt lgkmcnt(8)
	v_mfma_f32_32x32x16_bf16 v[64:79], v[222:225], v[8:11], v[64:79]
	ds_read_b64_tr_b16 v[8:9], v5 offset:15424
	ds_read_b64_tr_b16 v[10:11], v5 offset:17984
	v_max3_f32 v0, v0, v105, v120
	s_waitcnt lgkmcnt(8)
	v_mfma_f32_32x32x16_bf16 v[48:63], v[222:225], v[12:15], v[48:63]
	ds_read_b64_tr_b16 v[12:13], v5 offset:15488
	ds_read_b64_tr_b16 v[14:15], v5 offset:18048
	v_max3_f32 v3, v3, v122, v123
	v_max3_f32 v0, v0, v121, v108
	s_waitcnt lgkmcnt(8)
	v_mfma_f32_32x32x16_bf16 v[32:47], v[222:225], v[238:241], v[32:47]
	ds_read_b64_tr_b16 v[238:239], v5 offset:15552
	ds_read_b64_tr_b16 v[240:241], v5 offset:18112
	v_max3_f32 v3, v3, v110, v111
	v_max3_f32 v0, v0, v109, v124
	s_waitcnt lgkmcnt(8)
	v_mfma_f32_32x32x16_bf16 v[16:31], v[222:225], v[244:247], v[16:31]
	v_max3_f32 v3, v3, v126, v127
	s_waitcnt lgkmcnt(6)
	v_mfma_f32_32x32x16_bf16 v[64:79], v[230:233], v[248:251], v[64:79]
	v_max3_f32 v0, v0, v125, v3
	v_mov_b32_e32 v3, v0
	s_waitcnt lgkmcnt(4)
	v_mfma_f32_32x32x16_bf16 v[48:63], v[230:233], v[8:11], v[48:63]
	s_nop 1
	v_permlane32_swap_b32_e32 v0, v3
	s_waitcnt lgkmcnt(2)
	v_mfma_f32_32x32x16_bf16 v[32:47], v[230:233], v[12:15], v[32:47]
	v_max_f32_e32 v0, v0, v3
	s_waitcnt lgkmcnt(0)
	v_mfma_f32_32x32x16_bf16 v[16:31], v[230:233], v[238:241], v[16:31]
	s_setprio 0
	s_cmp_lg_u32 s75, 63
	s_cselect_b64 s[60:61], -1, 0
	s_cmp_eq_u32 s75, 63
	s_mov_b64 s[62:63], -1
	s_cbranch_scc1 .LBB0_2161_ab
	v_cmp_lt_f32_e32 vcc, s31, v0
	s_cbranch_vccz .LBB0_2170_ab
	v_max_f32_e32 v0, v0, v0
	v_max_f32_e32 v0, 0, v0

; #define ATT_BAR() asm volatile("s_waitcnt lgkmcnt(0)\n\ts_barrier" ::: "memory")
; #define ATT_BAR() asm volatile("s_waitcnt vmcnt(0) lgkmcnt(0)\n\ts_barrier" ::: "memory")
; template <int DQK>
; __device__ __forceinline__ void attn_pass4(LAS unsigned char* lds, const bf16* Qp, int qpitch, const bf16* Kp, int kpitch, const bf16* Vp, int vpitch, int q0, f32x16 (&o)[4], float (&rl)[16]) {
;     ...
;         for (int t = 0; t < NT; ++t) {
;             const int vnext = ATT_VNEXT(vcur);
;             if (t + 1 < NT) ATT_DMA(t + 1, (t + 1) & 1, vnext);
;             if (ATT_VIS(t)) { ATT_A(t); ATT_B(vcur); }
;             vcur = vnext;
;             ATT_BAR();
.Lnovis_ab:
	s_sub_i32 s61, s75, 0x7f
	s_cmp_gt_i32 s61, s25
	s_cbranch_scc1 .Lend_ab
	s_mul_i32 s94, s93, 0x5000
	v_add_u32_e32 v4, s94, v203
	v_add_u32_e32 v5, 0xc800, v4
	s_setprio 1
	ds_read_b64_tr_b16 v[238:239], v4 offset:51200
	ds_read_b64_tr_b16 v[240:241], v4 offset:53760
	ds_read_b64_tr_b16 v[244:245], v4 offset:51264
	ds_read_b64_tr_b16 v[246:247], v4 offset:53824
	ds_read_b64_tr_b16 v[248:249], v4 offset:51328
	ds_read_b64_tr_b16 v[250:251], v4 offset:53888
	ds_read_b64_tr_b16 v[8:9], v4 offset:51392
	ds_read_b64_tr_b16 v[10:11], v4 offset:53952
	ds_read_b64_tr_b16 v[12:13], v4 offset:56320
	ds_read_b64_tr_b16 v[14:15], v4 offset:58880
	v_exp_f32_e32 v206, v206
	v_exp_f32_e32 v207, v207
	v_exp_f32_e32 v208, v208
	v_exp_f32_e32 v209, v209
	v_exp_f32_e32 v210, v210
	v_exp_f32_e32 v211, v211
	v_exp_f32_e32 v212, v212
	v_exp_f32_e32 v213, v213
	v_add_f32_e32 v252, v206, v207
	v_add_f32_e32 v253, v208, v209
	v_add_f32_e32 v254, v210, v211
	v_add_f32_e32 v205, v212, v213
	s_nop 0
	v_cvt_pk_bf16_f32 v206, v206, v207
	v_cvt_pk_bf16_f32 v207, v208, v209
	v_cvt_pk_bf16_f32 v208, v210, v211
	v_cvt_pk_bf16_f32 v209, v212, v213
	s_nop 1
	s_waitcnt lgkmcnt(8)
	v_mfma_f32_32x32x16_bf16 v[64:79], v[206:209], v[238:241], v[64:79]
	ds_read_b64_tr_b16 v[238:239], v4 offset:56384
	ds_read_b64_tr_b16 v[240:241], v4 offset:58944
	v_exp_f32_e32 v214, v214
	v_exp_f32_e32 v215, v215
	v_exp_f32_e32 v216, v216
	v_exp_f32_e32 v217, v217
	v_exp_f32_e32 v218, v218
	v_exp_f32_e32 v219, v219
	s_waitcnt lgkmcnt(8)
	v_mfma_f32_32x32x16_bf16 v[48:63], v[206:209], v[244:247], v[48:63]
	ds_read_b64_tr_b16 v[244:245], v4 offset:56448
	ds_read_b64_tr_b16 v[246:247], v4 offset:59008
	v_exp_f32_e32 v220, v220
	v_exp_f32_e32 v221, v221
	v_add_f32_e32 v252, v252, v214
	v_add_f32_e32 v253, v253, v215
	v_add_f32_e32 v254, v254, v216
	s_waitcnt lgkmcnt(8)
	v_mfma_f32_32x32x16_bf16 v[32:47], v[206:209], v[248:251], v[32:47]
	ds_read_b64_tr_b16 v[248:249], v4 offset:56512
	ds_read_b64_tr_b16 v[250:251], v4 offset:59072
	v_add_f32_e32 v205, v205, v217
	v_add_f32_e32 v252, v252, v218
	v_add_f32_e32 v253, v253, v219
	v_add_f32_e32 v254, v254, v220
	v_add_f32_e32 v205, v205, v221
	s_waitcnt lgkmcnt(8)
	v_mfma_f32_32x32x16_bf16 v[16:31], v[206:209], v[8:11], v[16:31]
	ds_read_b64_tr_b16 v[8:9], v4 offset:61440
	ds_read_b64_tr_b16 v[10:11], v4 offset:64000
	v_cvt_pk_bf16_f32 v214, v214, v215
	v_cvt_pk_bf16_f32 v215, v216, v217
	v_cvt_pk_bf16_f32 v216, v218, v219
	v_cvt_pk_bf16_f32 v217, v220, v221
	s_nop 1
	s_waitcnt lgkmcnt(8)
	v_mfma_f32_32x32x16_bf16 v[64:79], v[214:217], v[12:15], v[64:79]
	ds_read_b64_tr_b16 v[12:13], v4 offset:61504
	ds_read_b64_tr_b16 v[14:15], v4 offset:64064
	v_exp_f32_e32 v222, v222
	v_exp_f32_e32 v223, v223
	v_exp_f32_e32 v224, v224
	v_exp_f32_e32 v225, v225
	v_exp_f32_e32 v226, v226
	v_exp_f32_e32 v227, v227
	s_waitcnt lgkmcnt(8)
	v_mfma_f32_32x32x16_bf16 v[48:63], v[214:217], v[238:241], v[48:63]
	ds_read_b64_tr_b16 v[238:239], v4 offset:61568
	ds_read_b64_tr_b16 v[240:241], v4 offset:64128
	v_exp_f32_e32 v228, v228
	v_exp_f32_e32 v229, v229
	v_add_f32_e32 v252, v252, v222
	v_add_f32_e32 v253, v253, v223
	v_add_f32_e32 v254, v254, v224
	s_waitcnt lgkmcnt(8)
	v_mfma_f32_32x32x16_bf16 v[32:47], v[214:217], v[244:247], v[32:47]
	ds_read_b64_tr_b16 v[244:245], v4 offset:61632
	ds_read_b64_tr_b16 v[246:247], v4 offset:64192
	v_add_f32_e32 v205, v205, v225
	v_add_f32_e32 v252, v252, v226
	v_add_f32_e32 v253, v253, v227
	v_add_f32_e32 v254, v254, v228
	v_add_f32_e32 v205, v205, v229
	s_waitcnt lgkmcnt(8)
	v_mfma_f32_32x32x16_bf16 v[16:31], v[214:217], v[248:251], v[16:31]
	ds_read_b64_tr_b16 v[248:249], v5 offset:15360
	ds_read_b64_tr_b16 v[250:251], v5 offset:17920
	v_cvt_pk_bf16_f32 v222, v222, v223
	v_cvt_pk_bf16_f32 v223, v224, v225
	v_cvt_pk_bf16_f32 v224, v226, v227
	v_cvt_pk_bf16_f32 v225, v228, v229
	s_nop 1
	s_waitcnt lgkmcnt(8)
	v_mfma_f32_32x32x16_bf16 v[64:79], v[222:225], v[8:11], v[64:79]
	ds_read_b64_tr_b16 v[8:9], v5 offset:15424
	ds_read_b64_tr_b16 v[10:11], v5 offset:17984
	v_exp_f32_e32 v230, v230
	v_exp_f32_e32 v231, v231
	v_exp_f32_e32 v232, v232
	v_exp_f32_e32 v233, v233
	v_exp_f32_e32 v234, v234
	v_exp_f32_e32 v235, v235
	s_waitcnt lgkmcnt(8)
	v_mfma_f32_32x32x16_bf16 v[48:63], v[222:225], v[12:15], v[48:63]
	ds_read_b64_tr_b16 v[12:13], v5 offset:15488
	ds_read_b64_tr_b16 v[14:15], v5 offset:18048
	v_exp_f32_e32 v236, v236
	v_exp_f32_e32 v237, v237
	v_add_f32_e32 v252, v252, v230
	v_add_f32_e32 v253, v253, v231
	v_add_f32_e32 v254, v254, v232
	s_waitcnt lgkmcnt(8)
	v_mfma_f32_32x32x16_bf16 v[32:47], v[222:225], v[238:241], v[32:47]
	ds_read_b64_tr_b16 v[238:239], v5 offset:15552
	ds_read_b64_tr_b16 v[240:241], v5 offset:18112
	v_add_f32_e32 v205, v205, v233
	v_add_f32_e32 v252, v252, v234
	v_add_f32_e32 v253, v253, v235
	v_add_f32_e32 v254, v254, v236
	v_add_f32_e32 v205, v205, v237
	s_waitcnt lgkmcnt(8)
	v_mfma_f32_32x32x16_bf16 v[16:31], v[222:225], v[244:247], v[16:31]
	v_cvt_pk_bf16_f32 v230, v230, v231
	v_cvt_pk_bf16_f32 v231, v232, v233
	v_cvt_pk_bf16_f32 v232, v234, v235
	v_cvt_pk_bf16_f32 v233, v236, v237
	s_nop 1
	s_waitcnt lgkmcnt(6)
	v_mfma_f32_32x32x16_bf16 v[64:79], v[230:233], v[248:251], v[64:79]
	v_add_f32_e32 v252, v252, v253
	s_waitcnt lgkmcnt(4)
	v_mfma_f32_32x32x16_bf16 v[48:63], v[230:233], v[8:11], v[48:63]
	v_add_f32_e32 v254, v254, v205
	s_waitcnt lgkmcnt(2)
	v_mfma_f32_32x32x16_bf16 v[32:47], v[230:233], v[12:15], v[32:47]
	v_add_f32_e32 v252, v252, v254
	s_waitcnt lgkmcnt(0)
	v_mfma_f32_32x32x16_bf16 v[16:31], v[230:233], v[238:241], v[16:31]
	v_add_f32_e32 v2, v2, v252
	s_setprio 0
.Lend_ab:
	s_add_i32 s75, s75, 64
	s_add_u32 s58, s58, 0x20000
	s_addc_u32 s59, s59, 0
	s_add_u32 s56, s56, 0x30000
	s_waitcnt vmcnt(0) lgkmcnt(0)
	s_barrier
	s_addc_u32 s57, s57, 0
	s_cmp_eq_u32 s69, s77
	s_mov_b32 s93, s78
	s_mov_b32 s78, s76
	s_mov_b32 s60, s77
	s_add_i32 s61, s77, 1
	s_cmp_eq_u32 s61, s69
	s_cbranch_scc0 .Lpipe_loop
	s_add_i32 s61, s78, 1
	s_cmp_lg_u32 s78, 2
	s_cselect_b32 s76, s61, 0
	s_add_i32 s77, s60, 1
	s_cmp_ge_u32 s77, s69
	s_cbranch_scc1 .LBB0_2155_fin
	s_bitcmp1_b32 s77, 0
	s_cselect_b32 s61, 0x6400, 0
	s_add_i32 s62, s61, s2
	s_add_i32 s62, s62, 0

	s_mov_b32 s63, m0
	s_mov_b32 m0, s62
	s_nop 0
	global_load_lds_dwordx4 v180, s[56:57]
	s_mov_b32 m0, s63
	s_add_i32 s62, s61, s72
	s_add_i32 s62, s62, 0

	s_mov_b32 s63, m0
	s_mov_b32 m0, s62
	s_nop 0
	global_load_lds_dwordx4 v182, s[56:57]
	s_mov_b32 m0, s63
	s_add_i32 s62, s61, s73

	s_add_i32 s62, s62, 0
	s_mov_b32 s63, m0
	s_mov_b32 m0, s62
	s_nop 0
	global_load_lds_dwordx4 v184, s[56:57]
	s_mov_b32 m0, s63
	s_andn2_b64 vcc, exec, s[12:13]
	s_cbranch_vccnz .LBB0_2154_fin
	s_add_i32 s61, s61, s74

	s_add_i32 s61, s61, 0
	s_mov_b32 s62, m0
	s_mov_b32 m0, s61
	s_nop 0
	global_load_lds_dwordx4 v190, s[56:57]
	s_mov_b32 m0, s62

; #define ATT_BAR() asm volatile("s_waitcnt lgkmcnt(0)\n\ts_barrier" ::: "memory")
; #define ATT_BAR() asm volatile("s_waitcnt vmcnt(0) lgkmcnt(0)\n\ts_barrier" ::: "memory")
; template <int DQK>
; __device__ __forceinline__ void attn_pass4(LAS unsigned char* lds, const bf16* Qp, int qpitch, const bf16* Kp, int kpitch, const bf16* Vp, int vpitch, int q0, f32x16 (&o)[4], float (&rl)[16]) {
;     ...
;     ATT_BAR();
.Lend_fin:
	s_add_i32 s75, s75, 64
	s_add_u32 s58, s58, 0x20000
	s_addc_u32 s59, s59, 0
	s_add_u32 s56, s56, 0x30000
	s_waitcnt vmcnt(0) lgkmcnt(0)
	s_barrier
	s_addc_u32 s57, s57, 0
	s_cmp_eq_u32 s69, s77
	s_mov_b32 s93, s78
	s_mov_b32 s78, s76
	s_mov_b32 s60, s77
	s_sub_i32 s61, s75, 0x7f
	s_cmp_gt_i32 s61, s25
	s_cbranch_scc1 .Lpipe_done
	s_mul_i32 s94, s93, 0x5000
	v_add_u32_e32 v4, s94, v203
	v_add_u32_e32 v5, 0xc800, v4
	s_setprio 1
	ds_read_b64_tr_b16 v[238:239], v4 offset:51200
	ds_read_b64_tr_b16 v[240:241], v4 offset:53760
	ds_read_b64_tr_b16 v[244:245], v4 offset:51264
	ds_read_b64_tr_b16 v[246:247], v4 offset:53824
	ds_read_b64_tr_b16 v[248:249], v4 offset:51328
	ds_read_b64_tr_b16 v[250:251], v4 offset:53888
	ds_read_b64_tr_b16 v[8:9], v4 offset:51392
	ds_read_b64_tr_b16 v[10:11], v4 offset:53952
	ds_read_b64_tr_b16 v[12:13], v4 offset:56320
	ds_read_b64_tr_b16 v[14:15], v4 offset:58880
	v_exp_f32_e32 v206, v206
	v_exp_f32_e32 v207, v207
	v_exp_f32_e32 v208, v208
	v_exp_f32_e32 v209, v209
	v_exp_f32_e32 v210, v210
	v_exp_f32_e32 v211, v211
	v_exp_f32_e32 v212, v212
	v_exp_f32_e32 v213, v213
	v_add_f32_e32 v252, v206, v207
	v_add_f32_e32 v253, v208, v209
	v_add_f32_e32 v254, v210, v211
	v_add_f32_e32 v205, v212, v213
	s_nop 0
	v_cvt_pk_bf16_f32 v206, v206, v207
	v_cvt_pk_bf16_f32 v207, v208, v209
	v_cvt_pk_bf16_f32 v208, v210, v211
	v_cvt_pk_bf16_f32 v209, v212, v213
	s_nop 1
	s_waitcnt lgkmcnt(8)
	v_mfma_f32_32x32x16_bf16 v[64:79], v[206:209], v[238:241], v[64:79]
	ds_read_b64_tr_b16 v[238:239], v4 offset:56384
	ds_read_b64_tr_b16 v[240:241], v4 offset:58944
	v_exp_f32_e32 v214, v214
	v_exp_f32_e32 v215, v215
	v_exp_f32_e32 v216, v216
	v_exp_f32_e32 v217, v217
	v_exp_f32_e32 v218, v218
	v_exp_f32_e32 v219, v219
	s_waitcnt lgkmcnt(8)
	v_mfma_f32_32x32x16_bf16 v[48:63], v[206:209], v[244:247], v[48:63]
	ds_read_b64_tr_b16 v[244:245], v4 offset:56448
	ds_read_b64_tr_b16 v[246:247], v4 offset:59008
	v_exp_f32_e32 v220, v220
	v_exp_f32_e32 v221, v221
	v_add_f32_e32 v252, v252, v214
	v_add_f32_e32 v253, v253, v215
	v_add_f32_e32 v254, v254, v216
	s_waitcnt lgkmcnt(8)
	v_mfma_f32_32x32x16_bf16 v[32:47], v[206:209], v[248:251], v[32:47]
	ds_read_b64_tr_b16 v[248:249], v4 offset:56512
	ds_read_b64_tr_b16 v[250:251], v4 offset:59072
	v_add_f32_e32 v205, v205, v217
	v_add_f32_e32 v252, v252, v218
	v_add_f32_e32 v253, v253, v219
	v_add_f32_e32 v254, v254, v220
	v_add_f32_e32 v205, v205, v221
	s_waitcnt lgkmcnt(8)
	v_mfma_f32_32x32x16_bf16 v[16:31], v[206:209], v[8:11], v[16:31]
	ds_read_b64_tr_b16 v[8:9], v4 offset:61440
	ds_read_b64_tr_b16 v[10:11], v4 offset:64000
	v_cvt_pk_bf16_f32 v214, v214, v215
	v_cvt_pk_bf16_f32 v215, v216, v217
	v_cvt_pk_bf16_f32 v216, v218, v219
	v_cvt_pk_bf16_f32 v217, v220, v221
	s_nop 1
	s_waitcnt lgkmcnt(8)
	v_mfma_f32_32x32x16_bf16 v[64:79], v[214:217], v[12:15], v[64:79]
	ds_read_b64_tr_b16 v[12:13], v4 offset:61504
	ds_read_b64_tr_b16 v[14:15], v4 offset:64064
	v_exp_f32_e32 v222, v222
	v_exp_f32_e32 v223, v223
	v_exp_f32_e32 v224, v224
	v_exp_f32_e32 v225, v225
	v_exp_f32_e32 v226, v226
	v_exp_f32_e32 v227, v227
	s_waitcnt lgkmcnt(8)
	v_mfma_f32_32x32x16_bf16 v[48:63], v[214:217], v[238:241], v[48:63]
	ds_read_b64_tr_b16 v[238:239], v4 offset:61568
	ds_read_b64_tr_b16 v[240:241], v4 offset:64128
	v_exp_f32_e32 v228, v228
	v_exp_f32_e32 v229, v229
	v_add_f32_e32 v252, v252, v222
	v_add_f32_e32 v253, v253, v223
	v_add_f32_e32 v254, v254, v224
	s_waitcnt lgkmcnt(8)
	v_mfma_f32_32x32x16_bf16 v[32:47], v[214:217], v[244:247], v[32:47]
	ds_read_b64_tr_b16 v[244:245], v4 offset:61632
	ds_read_b64_tr_b16 v[246:247], v4 offset:64192
	v_add_f32_e32 v205, v205, v225
	v_add_f32_e32 v252, v252, v226
	v_add_f32_e32 v253, v253, v227
	v_add_f32_e32 v254, v254, v228
	v_add_f32_e32 v205, v205, v229
	s_waitcnt lgkmcnt(8)
	v_mfma_f32_32x32x16_bf16 v[16:31], v[214:217], v[248:251], v[16:31]
	ds_read_b64_tr_b16 v[248:249], v5 offset:15360
	ds_read_b64_tr_b16 v[250:251], v5 offset:17920
	v_cvt_pk_bf16_f32 v222, v222, v223
	v_cvt_pk_bf16_f32 v223, v224, v225
	v_cvt_pk_bf16_f32 v224, v226, v227
	v_cvt_pk_bf16_f32 v225, v228, v229
	s_nop 1
	s_waitcnt lgkmcnt(8)
	v_mfma_f32_32x32x16_bf16 v[64:79], v[222:225], v[8:11], v[64:79]
	ds_read_b64_tr_b16 v[8:9], v5 offset:15424
	ds_read_b64_tr_b16 v[10:11], v5 offset:17984
	v_exp_f32_e32 v230, v230
	v_exp_f32_e32 v231, v231
	v_exp_f32_e32 v232, v232
	v_exp_f32_e32 v233, v233
	v_exp_f32_e32 v234, v234
	v_exp_f32_e32 v235, v235
	s_waitcnt lgkmcnt(8)
	v_mfma_f32_32x32x16_bf16 v[48:63], v[222:225], v[12:15], v[48:63]
	ds_read_b64_tr_b16 v[12:13], v5 offset:15488
	ds_read_b64_tr_b16 v[14:15], v5 offset:18048
	v_exp_f32_e32 v236, v236
	v_exp_f32_e32 v237, v237
	v_add_f32_e32 v252, v252, v230
	v_add_f32_e32 v253, v253, v231
	v_add_f32_e32 v254, v254, v232
	s_waitcnt lgkmcnt(8)
	v_mfma_f32_32x32x16_bf16 v[32:47], v[222:225], v[238:241], v[32:47]
	ds_read_b64_tr_b16 v[238:239], v5 offset:15552
	ds_read_b64_tr_b16 v[240:241], v5 offset:18112
	v_add_f32_e32 v205, v205, v233
	v_add_f32_e32 v252, v252, v234
	v_add_f32_e32 v253, v253, v235
	v_add_f32_e32 v254, v254, v236
	v_add_f32_e32 v205, v205, v237
	s_waitcnt lgkmcnt(8)
	v_mfma_f32_32x32x16_bf16 v[16:31], v[222:225], v[244:247], v[16:31]
	v_cvt_pk_bf16_f32 v230, v230, v231
	v_cvt_pk_bf16_f32 v231, v232, v233
	v_cvt_pk_bf16_f32 v232, v234, v235
	v_cvt_pk_bf16_f32 v233, v236, v237
	s_nop 1
	s_waitcnt lgkmcnt(6)
	v_mfma_f32_32x32x16_bf16 v[64:79], v[230:233], v[248:251], v[64:79]
	v_add_f32_e32 v252, v252, v253
	s_waitcnt lgkmcnt(4)
	v_mfma_f32_32x32x16_bf16 v[48:63], v[230:233], v[8:11], v[48:63]
	v_add_f32_e32 v254, v254, v205
	s_waitcnt lgkmcnt(2)
	v_mfma_f32_32x32x16_bf16 v[32:47], v[230:233], v[12:15], v[32:47]
	v_add_f32_e32 v252, v252, v254
	s_waitcnt lgkmcnt(0)
	v_mfma_f32_32x32x16_bf16 v[16:31], v[230:233], v[238:241], v[16:31]
	v_add_f32_e32 v2, v2, v252
	s_setprio 0
.Lpipe_done:
.LBB0_2171:
	s_mov_b64 s[56:57], 0
